# EpiUp rewrite (fmac_dpp) + edge-fix 'up' row requested early + context-row slab folds with 7-8 loads in flight (were 32 load-wait-add steps)
# speedup vs baseline: 1.0135x; 1.0014x over previous
; #define GAS __attribute__((address_space(1)))
;     ...
;         if (row >= ML && nslab > 0) {
;             const GAS float* sl = WSP(float, WS_SLAB) + (size_t)(row - ML) * DM; GAS float* xw = WSP(float, WS_XC) + (size_t)(row - ML) * DM;
;             for (int ks = 0; ks < nslab; ++ks)
; #pragma unroll
;                 for (int j = 0; j < 8; ++j) v[j] += *(const GAS f32x4*)(sl + (size_t)ks * MC * DM + 4 * (F.lane + 64 * j));
; #pragma unroll
;             for (int j = 0; j < 8; ++j) *(GAS f32x4*)(xw + 4 * (F.lane + 64 * j)) = v[j];
;         }
.LBB0_151:
	s_add_i32 s12, s50, 0x8000
	s_cmp_lt_i32 s12, 0x8000
	s_cbranch_scc1 .LBB0_148
	s_lshl_b64 s[4:5], s[50:51], 13
	s_add_u32 s10, s16, s4
	s_addc_u32 s11, s17, s5
	global_load_dwordx4 v[98:101], v85, s[10:11]
	global_load_dwordx4 v[102:105], v85, s[10:11] offset:1024
	global_load_dwordx4 v[106:109], v85, s[10:11] offset:2048
	global_load_dwordx4 v[110:113], v85, s[10:11] offset:3072
	global_load_dwordx4 v[114:117], v89, s[10:11]
	global_load_dwordx4 v[118:121], v90, s[10:11]
	global_load_dwordx4 v[122:125], v91, s[10:11]
	global_load_dwordx4 v[136:139], v92, s[10:11]
	s_waitcnt vmcnt(7)
	v_pk_add_f32 v[60:61], v[60:61], v[98:99]
	v_pk_add_f32 v[62:63], v[62:63], v[100:101]
	s_add_u32 s22, s10, 0x400000
	s_addc_u32 s23, s11, 0
	global_load_dwordx4 v[98:101], v85, s[22:23]
	s_waitcnt vmcnt(7)
	v_pk_add_f32 v[56:57], v[56:57], v[102:103]
	v_pk_add_f32 v[58:59], v[58:59], v[104:105]
	global_load_dwordx4 v[102:105], v85, s[22:23] offset:1024
	s_waitcnt vmcnt(7)
	v_pk_add_f32 v[52:53], v[52:53], v[106:107]
	v_pk_add_f32 v[54:55], v[54:55], v[108:109]
	global_load_dwordx4 v[106:109], v85, s[22:23] offset:2048
	s_waitcnt vmcnt(7)
	v_pk_add_f32 v[44:45], v[44:45], v[110:111]
	v_pk_add_f32 v[46:47], v[46:47], v[112:113]
	global_load_dwordx4 v[110:113], v85, s[22:23] offset:3072
	s_waitcnt vmcnt(7)
	v_pk_add_f32 v[40:41], v[40:41], v[114:115]
	v_pk_add_f32 v[42:43], v[42:43], v[116:117]
	global_load_dwordx4 v[114:117], v89, s[22:23]
	s_waitcnt vmcnt(7)
	v_pk_add_f32 v[36:37], v[36:37], v[118:119]
	v_pk_add_f32 v[38:39], v[38:39], v[120:121]
	global_load_dwordx4 v[118:121], v90, s[22:23]
	s_waitcnt vmcnt(7)
	v_pk_add_f32 v[32:33], v[32:33], v[122:123]
	v_pk_add_f32 v[34:35], v[34:35], v[124:125]
	global_load_dwordx4 v[122:125], v91, s[22:23]
	s_waitcnt vmcnt(7)
	v_pk_add_f32 v[48:49], v[48:49], v[136:137]
	v_pk_add_f32 v[50:51], v[50:51], v[138:139]
	global_load_dwordx4 v[136:139], v92, s[22:23]
	s_waitcnt vmcnt(7)
	v_pk_add_f32 v[60:61], v[60:61], v[98:99]
	v_pk_add_f32 v[62:63], v[62:63], v[100:101]
	s_add_u32 s22, s10, 0x800000
	s_addc_u32 s23, s11, 0
	global_load_dwordx4 v[98:101], v85, s[22:23]
	s_waitcnt vmcnt(7)
	v_pk_add_f32 v[56:57], v[56:57], v[102:103]
	v_pk_add_f32 v[58:59], v[58:59], v[104:105]
	global_load_dwordx4 v[102:105], v85, s[22:23] offset:1024
	s_waitcnt vmcnt(7)
	v_pk_add_f32 v[52:53], v[52:53], v[106:107]
	v_pk_add_f32 v[54:55], v[54:55], v[108:109]
	global_load_dwordx4 v[106:109], v85, s[22:23] offset:2048
	s_waitcnt vmcnt(7)
	v_pk_add_f32 v[44:45], v[44:45], v[110:111]
	v_pk_add_f32 v[46:47], v[46:47], v[112:113]
	global_load_dwordx4 v[110:113], v85, s[22:23] offset:3072
	s_waitcnt vmcnt(7)
	v_pk_add_f32 v[40:41], v[40:41], v[114:115]
	v_pk_add_f32 v[42:43], v[42:43], v[116:117]
	global_load_dwordx4 v[114:117], v89, s[22:23]
	s_waitcnt vmcnt(7)
	v_pk_add_f32 v[36:37], v[36:37], v[118:119]
	v_pk_add_f32 v[38:39], v[38:39], v[120:121]
	global_load_dwordx4 v[118:121], v90, s[22:23]
	s_waitcnt vmcnt(7)
	v_pk_add_f32 v[32:33], v[32:33], v[122:123]
	v_pk_add_f32 v[34:35], v[34:35], v[124:125]
	global_load_dwordx4 v[122:125], v91, s[22:23]
	s_waitcnt vmcnt(7)
	v_pk_add_f32 v[48:49], v[48:49], v[136:137]
	v_pk_add_f32 v[50:51], v[50:51], v[138:139]
	global_load_dwordx4 v[136:139], v92, s[22:23]
	s_waitcnt vmcnt(7)
	v_pk_add_f32 v[60:61], v[60:61], v[98:99]
	v_pk_add_f32 v[62:63], v[62:63], v[100:101]
	s_add_u32 s22, s10, 0xc00000
	s_addc_u32 s23, s11, 0
	global_load_dwordx4 v[98:101], v85, s[22:23]
	s_waitcnt vmcnt(7)
	v_pk_add_f32 v[56:57], v[56:57], v[102:103]
	v_pk_add_f32 v[58:59], v[58:59], v[104:105]
	global_load_dwordx4 v[102:105], v85, s[22:23] offset:1024
	s_waitcnt vmcnt(7)
	v_pk_add_f32 v[52:53], v[52:53], v[106:107]
	v_pk_add_f32 v[54:55], v[54:55], v[108:109]
	global_load_dwordx4 v[106:109], v85, s[22:23] offset:2048
	s_waitcnt vmcnt(7)
	v_pk_add_f32 v[44:45], v[44:45], v[110:111]
	v_pk_add_f32 v[46:47], v[46:47], v[112:113]
	global_load_dwordx4 v[110:113], v85, s[22:23] offset:3072
	s_waitcnt vmcnt(7)
	v_pk_add_f32 v[40:41], v[40:41], v[114:115]
	v_pk_add_f32 v[42:43], v[42:43], v[116:117]
	global_load_dwordx4 v[114:117], v89, s[22:23]
	s_waitcnt vmcnt(7)
	v_pk_add_f32 v[36:37], v[36:37], v[118:119]
	v_pk_add_f32 v[38:39], v[38:39], v[120:121]
	global_load_dwordx4 v[118:121], v90, s[22:23]
	s_waitcnt vmcnt(7)
	v_pk_add_f32 v[32:33], v[32:33], v[122:123]
	v_pk_add_f32 v[34:35], v[34:35], v[124:125]
	global_load_dwordx4 v[122:125], v91, s[22:23]
	s_waitcnt vmcnt(7)
	v_pk_add_f32 v[48:49], v[48:49], v[136:137]
	v_pk_add_f32 v[50:51], v[50:51], v[138:139]
	global_load_dwordx4 v[136:139], v92, s[22:23]
	s_waitcnt vmcnt(7)
	v_pk_add_f32 v[60:61], v[60:61], v[98:99]
	v_pk_add_f32 v[62:63], v[62:63], v[100:101]
	s_waitcnt vmcnt(6)
	v_pk_add_f32 v[56:57], v[56:57], v[102:103]
	v_pk_add_f32 v[58:59], v[58:59], v[104:105]
	s_waitcnt vmcnt(5)
	v_pk_add_f32 v[52:53], v[52:53], v[106:107]
	v_pk_add_f32 v[54:55], v[54:55], v[108:109]
	s_waitcnt vmcnt(4)
	v_pk_add_f32 v[44:45], v[44:45], v[110:111]
	v_pk_add_f32 v[46:47], v[46:47], v[112:113]
	s_waitcnt vmcnt(3)
	v_pk_add_f32 v[40:41], v[40:41], v[114:115]
	v_pk_add_f32 v[42:43], v[42:43], v[116:117]
	s_waitcnt vmcnt(2)
	v_pk_add_f32 v[36:37], v[36:37], v[118:119]
	v_pk_add_f32 v[38:39], v[38:39], v[120:121]
	s_waitcnt vmcnt(1)
	v_pk_add_f32 v[32:33], v[32:33], v[122:123]
	v_pk_add_f32 v[34:35], v[34:35], v[124:125]
	s_waitcnt vmcnt(0)
	v_pk_add_f32 v[48:49], v[48:49], v[136:137]
	v_pk_add_f32 v[50:51], v[50:51], v[138:139]
	s_add_u32 s22, s10, 0x800000
	s_addc_u32 s23, s11, 0
	s_add_u32 s10, s10, 0xc00000
	s_addc_u32 s11, s11, 0
	s_add_u32 s4, s14, s4
	s_addc_u32 s5, s15, s5
	global_store_dwordx4 v85, v[60:63], s[4:5]
	global_store_dwordx4 v85, v[56:59], s[4:5] offset:1024
	global_store_dwordx4 v85, v[52:55], s[4:5] offset:2048
	global_store_dwordx4 v85, v[44:47], s[4:5] offset:3072
	global_store_dwordx4 v89, v[40:43], s[4:5]
	global_store_dwordx4 v90, v[36:39], s[4:5]
	global_store_dwordx4 v91, v[32:35], s[4:5]
	global_store_dwordx4 v92, v[48:51], s[4:5]
	s_branch .LBB0_148

; #define GAS __attribute__((address_space(1)))
;     ...
;         if (row >= ML && nslab > 0) {
;             const GAS float* sl = WSP(float, WS_SLAB) + (size_t)(row - ML) * DM; GAS float* xw = WSP(float, WS_XC) + (size_t)(row - ML) * DM;
;             for (int ks = 0; ks < nslab; ++ks)
; #pragma unroll
;                 for (int j = 0; j < 8; ++j) v[j] += *(const GAS f32x4*)(sl + (size_t)ks * MC * DM + 4 * (F.lane + 64 * j));
; #pragma unroll
;             for (int j = 0; j < 8; ++j) *(GAS f32x4*)(xw + 4 * (F.lane + 64 * j)) = v[j];
;         }
.LBB0_1387:
	s_add_i32 s10, s50, 0x8000
	s_cmp_lt_i32 s10, 0x8000
	s_cbranch_scc1 .LBB0_1384
	s_lshl_b64 s[6:7], s[50:51], 13
	s_add_u32 s8, s13, s6
	s_addc_u32 s9, s16, s7
	global_load_dwordx4 v[92:95], v84, s[8:9]
	global_load_dwordx4 v[96:99], v84, s[8:9] offset:1024
	global_load_dwordx4 v[100:103], v84, s[8:9] offset:2048
	global_load_dwordx4 v[104:107], v84, s[8:9] offset:3072
	global_load_dwordx4 v[108:111], v88, s[8:9]
	global_load_dwordx4 v[112:115], v89, s[8:9]
	global_load_dwordx4 v[116:119], v90, s[8:9]
	s_waitcnt vmcnt(6)
	v_pk_add_f32 v[60:61], v[60:61], v[92:93]
	v_pk_add_f32 v[62:63], v[62:63], v[94:95]
	global_load_dwordx4 v[92:95], v91, s[8:9]
	s_waitcnt vmcnt(6)
	v_pk_add_f32 v[56:57], v[56:57], v[96:97]
	v_pk_add_f32 v[58:59], v[58:59], v[98:99]
	s_add_u32 s20, s8, 0x400000
	s_addc_u32 s21, s9, 0
	global_load_dwordx4 v[96:99], v84, s[20:21]
	s_waitcnt vmcnt(6)
	v_pk_add_f32 v[52:53], v[52:53], v[100:101]
	v_pk_add_f32 v[54:55], v[54:55], v[102:103]
	global_load_dwordx4 v[100:103], v84, s[20:21] offset:1024
	s_waitcnt vmcnt(6)
	v_pk_add_f32 v[44:45], v[44:45], v[104:105]
	v_pk_add_f32 v[46:47], v[46:47], v[106:107]
	global_load_dwordx4 v[104:107], v84, s[20:21] offset:2048
	s_waitcnt vmcnt(6)
	v_pk_add_f32 v[40:41], v[40:41], v[108:109]
	v_pk_add_f32 v[42:43], v[42:43], v[110:111]
	global_load_dwordx4 v[108:111], v84, s[20:21] offset:3072
	s_waitcnt vmcnt(6)
	v_pk_add_f32 v[36:37], v[36:37], v[112:113]
	v_pk_add_f32 v[38:39], v[38:39], v[114:115]
	global_load_dwordx4 v[112:115], v88, s[20:21]
	s_waitcnt vmcnt(6)
	v_pk_add_f32 v[32:33], v[32:33], v[116:117]
	v_pk_add_f32 v[34:35], v[34:35], v[118:119]
	global_load_dwordx4 v[116:119], v89, s[20:21]
	s_waitcnt vmcnt(6)
	v_pk_add_f32 v[48:49], v[48:49], v[92:93]
	v_pk_add_f32 v[50:51], v[50:51], v[94:95]
	global_load_dwordx4 v[92:95], v90, s[20:21]
	s_waitcnt vmcnt(6)
	v_pk_add_f32 v[60:61], v[60:61], v[96:97]
	v_pk_add_f32 v[62:63], v[62:63], v[98:99]
	global_load_dwordx4 v[96:99], v91, s[20:21]
	s_waitcnt vmcnt(6)
	v_pk_add_f32 v[56:57], v[56:57], v[100:101]
	v_pk_add_f32 v[58:59], v[58:59], v[102:103]
	s_add_u32 s20, s8, 0x800000
	s_addc_u32 s21, s9, 0
	global_load_dwordx4 v[100:103], v84, s[20:21]
	s_waitcnt vmcnt(6)
	v_pk_add_f32 v[52:53], v[52:53], v[104:105]
	v_pk_add_f32 v[54:55], v[54:55], v[106:107]
	global_load_dwordx4 v[104:107], v84, s[20:21] offset:1024
	s_waitcnt vmcnt(6)
	v_pk_add_f32 v[44:45], v[44:45], v[108:109]
	v_pk_add_f32 v[46:47], v[46:47], v[110:111]
	global_load_dwordx4 v[108:111], v84, s[20:21] offset:2048
	s_waitcnt vmcnt(6)
	v_pk_add_f32 v[40:41], v[40:41], v[112:113]
	v_pk_add_f32 v[42:43], v[42:43], v[114:115]
	global_load_dwordx4 v[112:115], v84, s[20:21] offset:3072
	s_waitcnt vmcnt(6)
	v_pk_add_f32 v[36:37], v[36:37], v[116:117]
	v_pk_add_f32 v[38:39], v[38:39], v[118:119]
	global_load_dwordx4 v[116:119], v88, s[20:21]
	s_waitcnt vmcnt(6)
	v_pk_add_f32 v[32:33], v[32:33], v[92:93]
	v_pk_add_f32 v[34:35], v[34:35], v[94:95]
	global_load_dwordx4 v[92:95], v89, s[20:21]
	s_waitcnt vmcnt(6)
	v_pk_add_f32 v[48:49], v[48:49], v[96:97]
	v_pk_add_f32 v[50:51], v[50:51], v[98:99]
	global_load_dwordx4 v[96:99], v90, s[20:21]
	s_waitcnt vmcnt(6)
	v_pk_add_f32 v[60:61], v[60:61], v[100:101]
	v_pk_add_f32 v[62:63], v[62:63], v[102:103]
	global_load_dwordx4 v[100:103], v91, s[20:21]
	s_waitcnt vmcnt(6)
	v_pk_add_f32 v[56:57], v[56:57], v[104:105]
	v_pk_add_f32 v[58:59], v[58:59], v[106:107]
	s_add_u32 s20, s8, 0xc00000
	s_addc_u32 s21, s9, 0
	global_load_dwordx4 v[104:107], v84, s[20:21]
	s_waitcnt vmcnt(6)
	v_pk_add_f32 v[52:53], v[52:53], v[108:109]
	v_pk_add_f32 v[54:55], v[54:55], v[110:111]
	global_load_dwordx4 v[108:111], v84, s[20:21] offset:1024
	s_waitcnt vmcnt(6)
	v_pk_add_f32 v[44:45], v[44:45], v[112:113]
	v_pk_add_f32 v[46:47], v[46:47], v[114:115]
	global_load_dwordx4 v[112:115], v84, s[20:21] offset:2048
	s_waitcnt vmcnt(6)
	v_pk_add_f32 v[40:41], v[40:41], v[116:117]
	v_pk_add_f32 v[42:43], v[42:43], v[118:119]
	global_load_dwordx4 v[116:119], v84, s[20:21] offset:3072
	s_waitcnt vmcnt(6)
	v_pk_add_f32 v[36:37], v[36:37], v[92:93]
	v_pk_add_f32 v[38:39], v[38:39], v[94:95]
	global_load_dwordx4 v[92:95], v88, s[20:21]
	s_waitcnt vmcnt(6)
	v_pk_add_f32 v[32:33], v[32:33], v[96:97]
	v_pk_add_f32 v[34:35], v[34:35], v[98:99]
	global_load_dwordx4 v[96:99], v89, s[20:21]
	s_waitcnt vmcnt(6)
	v_pk_add_f32 v[48:49], v[48:49], v[100:101]
	v_pk_add_f32 v[50:51], v[50:51], v[102:103]
	global_load_dwordx4 v[100:103], v90, s[20:21]
	s_waitcnt vmcnt(6)
	v_pk_add_f32 v[60:61], v[60:61], v[104:105]
	v_pk_add_f32 v[62:63], v[62:63], v[106:107]
	global_load_dwordx4 v[104:107], v91, s[20:21]
	s_waitcnt vmcnt(6)
	v_pk_add_f32 v[56:57], v[56:57], v[108:109]
	v_pk_add_f32 v[58:59], v[58:59], v[110:111]
	s_waitcnt vmcnt(5)
	v_pk_add_f32 v[52:53], v[52:53], v[112:113]
	v_pk_add_f32 v[54:55], v[54:55], v[114:115]
	s_waitcnt vmcnt(4)
	v_pk_add_f32 v[44:45], v[44:45], v[116:117]
	v_pk_add_f32 v[46:47], v[46:47], v[118:119]
	s_waitcnt vmcnt(3)
	v_pk_add_f32 v[40:41], v[40:41], v[92:93]
	v_pk_add_f32 v[42:43], v[42:43], v[94:95]
	s_waitcnt vmcnt(2)
	v_pk_add_f32 v[36:37], v[36:37], v[96:97]
	v_pk_add_f32 v[38:39], v[38:39], v[98:99]
	s_waitcnt vmcnt(1)
	v_pk_add_f32 v[32:33], v[32:33], v[100:101]
	v_pk_add_f32 v[34:35], v[34:35], v[102:103]
	s_waitcnt vmcnt(0)
	v_pk_add_f32 v[48:49], v[48:49], v[104:105]
	v_pk_add_f32 v[50:51], v[50:51], v[106:107]
	s_add_u32 s20, s8, 0x800000
	s_addc_u32 s21, s9, 0
	s_add_u32 s8, s8, 0xc00000
	s_addc_u32 s9, s9, 0
	s_add_u32 s6, s0, s6
	s_addc_u32 s7, s2, s7
	global_store_dwordx4 v84, v[60:63], s[6:7]
	global_store_dwordx4 v84, v[56:59], s[6:7] offset:1024
	global_store_dwordx4 v84, v[52:55], s[6:7] offset:2048
	global_store_dwordx4 v84, v[44:47], s[6:7] offset:3072
	global_store_dwordx4 v88, v[40:43], s[6:7]
	global_store_dwordx4 v89, v[36:39], s[6:7]
	global_store_dwordx4 v90, v[32:35], s[6:7]
	global_store_dwordx4 v91, v[48:51], s[6:7]
	s_branch .LBB0_1384

; #define GAS __attribute__((address_space(1)))
; __device__ __forceinline__ unsigned pk2(float lo, float hi) { return f2bf(lo) | (f2bf(hi) << 16); }
; __device__ __forceinline__ void edge_fix_phase(Frame& F, int l, bool with_ctx) {
;     ...
;     for (int i = F.vcu * NTHR + F.tid; i < total; i += F.G * NTHR) {
;         const int e = i / (DFF / 4), c = (i % (DFF / 4)) * 4;
;         const int r = (e >> 1) * 64 + (e & 1) * 63;
;         f32x4 p = *(const GAS f32x4*)(EP + (size_t)e * DFF + c);
;         if (e & 1) { const int nr = r + 1; if (nr != SEQ && nr != ML && nr != ML + CTXL && nr != MT) p += *(const GAS f32x4*)(cw + 2 * DFF + c) * *(const GAS f32x4*)(EG + (size_t)(e + 1) * DFF + c); }
;         else { if (r != 0 && r != SEQ && r != ML && r != ML + CTXL) p += *(const GAS f32x4*)(cw + c) * *(const GAS f32x4*)(EG + (size_t)(e - 1) * DFF + c); }
;         const f32x4 up = *(const GAS f32x4*)(EU + (size_t)e * DFF + c);
;         v2u o; o.x = pk2(gelu_tanh(p.x) * up.x, gelu_tanh(p.y) * up.y); o.y = pk2(gelu_tanh(p.z) * up.z, gelu_tanh(p.w) * up.w);
;         *(GAS v2u*)(HID + (size_t)r * DFF + c) = o;
.LBB0_1596:
	s_or_b64 exec, exec, s[6:7]
	s_waitcnt vmcnt(0)
	v_mov_b32_e32 v6, v24
	v_mov_b32_e32 v7, v25
	v_mov_b32_e32 v8, v26
	v_mov_b32_e32 v9, v27
	v_mul_f32_e32 v13, 0x3d372713, v0
	v_fma_f32 v13, v0, v13, 1.0
	v_mul_f32_e32 v13, v0, v13
	v_mul_f32_e32 v13, 0xc0135761, v13
	v_exp_f32_e32 v13, v13
	v_mov_b32_e32 v18, v0
	v_mov_b32_e32 v19, v2
	s_movk_i32 s6, 0x2c00
	v_add_f32_e32 v13, 1.0, v13
	v_rcp_f32_e32 v14, v13
	v_mul_f32_e32 v13, 0x3d372713, v1
	v_fma_f32 v13, v1, v13, 1.0
	v_mul_f32_e32 v13, v1, v13
	v_mul_f32_e32 v13, 0xc0135761, v13
	v_exp_f32_e32 v13, v13
	v_add_u32_e32 v11, s30, v11
	v_add_f32_e32 v13, 1.0, v13
	v_rcp_f32_e32 v16, v13
	v_mul_f32_e32 v13, 0x3d372713, v2
	v_fma_f32 v13, v2, v13, 1.0
	v_mul_f32_e32 v13, v2, v13
	v_mul_f32_e32 v13, 0xc0135761, v13
	v_exp_f32_e32 v13, v13
	v_mov_b32_e32 v2, v1
	v_add_f32_e32 v13, 1.0, v13
	v_rcp_f32_e32 v15, v13
	v_mul_f32_e32 v13, 0x3d372713, v3
	v_fma_f32 v13, v3, v13, 1.0
	v_mul_f32_e32 v13, v3, v13
	v_mul_f32_e32 v13, 0xc0135761, v13
	v_exp_f32_e32 v13, v13
	v_pk_mul_f32 v[14:15], v[18:19], v[14:15]
	v_add_f32_e32 v13, 1.0, v13
	v_rcp_f32_e32 v17, v13
	v_mov_b32_e32 v19, v8
	v_pk_mul_f32 v[0:1], v[2:3], v[16:17]
	v_mov_b32_e32 v8, v7
	v_mov_b32_e32 v18, v6
	v_pk_mul_f32 v[0:1], v[8:9], v[0:1]
	v_pk_mul_f32 v[14:15], v[18:19], v[14:15]
	v_and_b32_sdwa v6, v1, v217 dst_sel:DWORD dst_unused:UNUSED_PAD src0_sel:WORD_1 src1_sel:DWORD
	v_and_b32_sdwa v7, v0, v217 dst_sel:DWORD dst_unused:UNUSED_PAD src0_sel:WORD_1 src1_sel:DWORD
	v_and_b32_sdwa v2, v15, v217 dst_sel:DWORD dst_unused:UNUSED_PAD src0_sel:WORD_1 src1_sel:DWORD
	v_and_b32_sdwa v3, v14, v217 dst_sel:DWORD dst_unused:UNUSED_PAD src0_sel:WORD_1 src1_sel:DWORD
	v_add3_u32 v1, v1, v6, s61
	v_add3_u32 v0, v0, v7, s61
	v_add3_u32 v3, v14, v3, s61
	v_add3_u32 v2, v15, v2, s61
	v_and_b32_e32 v1, 0xffff0000, v1
	v_and_b32_e32 v0, 0xffff0000, v0
	v_or_b32_sdwa v1, v1, v2 dst_sel:DWORD dst_unused:UNUSED_PAD src0_sel:DWORD src1_sel:WORD_1
	v_or_b32_sdwa v0, v0, v3 dst_sel:DWORD dst_unused:UNUSED_PAD src0_sel:DWORD src1_sel:WORD_1
	v_mov_b64_e32 v[2:3], s[16:17]
	v_mad_i64_i32 v[2:3], s[6:7], v12, s6, v[2:3]
	v_readlane_b32 s6, v254, 46
	v_lshl_add_u64 v[2:3], v[4:5], 1, v[2:3]
	global_store_dwordx2 v[2:3], v[0:1], off
	v_add_u32_e32 v10, s6, v10
	v_cmp_le_i32_e32 vcc, s2, v10
	s_or_b64 s[20:21], vcc, s[20:21]
	s_andn2_b64 exec, exec, s[20:21]
	s_cbranch_execz .LBB0_1593
.LBB0_1597:
	s_mov_b32 s6, 0x2e8ba2e9
	v_mul_hi_i32 v0, v10, s6
	v_lshrrev_b32_e32 v1, 31, v0
	v_ashrrev_i32_e32 v0, 8, v0
	v_add_u32_e32 v13, v0, v1
	v_mul_i32_i24_e32 v0, 0x580, v13
	v_lshlrev_b32_e32 v0, 2, v0
	v_and_b32_e32 v8, 1, v13
	v_sub_u32_e32 v4, v11, v0
	v_lshlrev_b32_e32 v14, 5, v13
	v_mul_u32_u24_e32 v0, 63, v8
	s_movk_i32 s6, 0xffc0
	v_mul_hi_i32_i24_e32 v7, 0x1600, v13
	v_mul_i32_i24_e32 v6, 0x1600, v13
	v_and_or_b32 v12, v14, s6, v0
	v_lshl_add_u64 v[0:1], v[6:7], 2, s[10:11]
	v_ashrrev_i32_e32 v5, 31, v4
	v_lshl_add_u64 v[0:1], v[4:5], 2, v[0:1]
	global_load_dwordx4 v[0:3], v[0:1], off
	v_lshl_add_u64 v[28:29], v[6:7], 2, s[12:13]
	v_lshl_add_u64 v[28:29], v[4:5], 2, v[28:29]
	global_load_dwordx4 v[24:27], v[28:29], off
	v_cmp_eq_u32_e32 vcc, 1, v8
	s_mov_b64 s[22:23], 0
	s_and_saveexec_b64 s[6:7], vcc
	s_xor_b64 s[6:7], exec, s[6:7]
	s_cbranch_execz .LBB0_1611
	s_mov_b32 s22, 0x80fe
	v_cmp_lt_i32_e32 vcc, s22, v12
	s_mov_b64 s[22:23], 0
	s_and_saveexec_b64 s[24:25], vcc
	s_xor_b64 s[24:25], exec, s[24:25]
	s_cbranch_execz .LBB0_1604
	s_mov_b32 s22, 0x81fe
	v_cmp_lt_i32_e32 vcc, s22, v12
	s_mov_b64 s[22:23], 0
	s_and_saveexec_b64 s[26:27], vcc
	s_xor_b64 s[26:27], exec, s[26:27]
	s_mov_b32 s22, 0x81ff
	v_cmp_ne_u32_e32 vcc, s22, v12
	s_and_b64 s[22:23], vcc, exec
	s_andn2_saveexec_b64 s[26:27], s[26:27]
	s_mov_b32 s28, 0x80ff
	v_cmp_ne_u32_e32 vcc, s28, v12
	s_andn2_b64 s[22:23], s[22:23], exec
	s_and_b64 s[28:29], vcc, exec
	s_or_b64 s[22:23], s[22:23], s[28:29]
	s_or_b64 exec, exec, s[26:27]
	s_and_b64 s[22:23], s[22:23], exec
